# NSA loops: static s_setprio 1 for the second (skewed) virtual block from the selected loop to the end of the window loop, replacing per-cluster priority toggling
# baseline (speedup 1.0000x reference)
; DEVI void nsa_item(const Params& p, int l, int item, char* lds_raw, volatile int* nsa_cnt) {
;     ...
; #pragma unroll
;     for (int g = 0; g < 2; ++g) {
;       const float lsum = attn_rowsum(st, g);
;       float sc = (lsum > 0.f ? 1.f / lsum : 0.f) * gate[g][2];
; #pragma unroll
;       for (int d = 0; d < 4; ++d) fin[g][d] += st.o[g][d] * sc;
;     }
;   }
.Lwin_skew_out:
	s_setprio 0
	s_nop 3
	v_mov_b32_e32 v135, v138

; DEVI int vhalf() { int t = threadIdx.x >> 8; t = __builtin_amdgcn_readfirstlane(t); return t; }
; DEVI void nsa_item(const Params& p, int l, int item, char* lds_raw, volatile int* nsa_cnt) {
;     ...
;   {
;     AttnState st;
;     attn_init(st);
;     const bfu* kbase = proj + tokbase * LDP + C_KS + h * 64;
;     const bfu* vbase = (const bfu*)(p.ws + OFF_VST) + ((long)b * 128 + h * 64) * SEQ;
;     unsigned rem = ormask & ((2u << qt) - 1u);
;     if (tid == 0) nsa_cnt[vhalf()] = __popc(rem);
;     __syncthreads();
;     const int niter = max(nsa_cnt[0], nsa_cnt[1]);
;     int j = __ffs(rem) - 1;
;     KV_LOAD(kbase, vbase, j);
.LBB0_500:
	s_or_b64 exec, exec, s[0:1]
	s_mov_b64 s[0:1], src_shared_base
	v_mov_b32_e32 v179, s1
	v_mov_b32_e32 v181, s1
	s_waitcnt lgkmcnt(0)
	s_barrier
	ds_read_b32 v82, v178
	ds_read_b32 v84, v180
	s_mul_i32 s0, s20, 0xc00000
	v_ashrrev_i32_e32 v186, 3, v83
	s_add_u32 s0, s6, s0
	v_add_u32_e32 v142, 32, v186
	s_addc_u32 s1, s7, 0
	v_mov_b32_e32 v66, v1
	v_mov_b32_e32 v67, v1
	v_mov_b32_e32 v68, v1
	v_mov_b32_e32 v69, v1
	v_ashrrev_i32_e32 v143, 31, v142
	s_add_u32 s36, s0, s11
	v_ashrrev_i32_e32 v187, 31, v186
	v_mov_b64_e32 v[62:63], v[66:67]
	v_mov_b64_e32 v[58:59], v[66:67]
	v_mov_b64_e32 v[50:51], v[66:67]
	v_mov_b64_e32 v[80:81], v[68:69]
	v_mov_b64_e32 v[76:77], v[68:69]
	v_mov_b64_e32 v[72:73], v[68:69]
	v_mov_b64_e32 v[54:55], v[66:67]
	v_mov_b64_e32 v[104:105], v[68:69]
	v_lshlrev_b64 v[146:147], 11, v[142:143]
	s_addc_u32 s37, s1, 0
	s_lshl_b32 s0, s20, 18
	s_lshl_b32 s1, s23, 17
	v_mov_b64_e32 v[108:109], v[68:69]
	v_mov_b32_e32 v179, 0
	v_mov_b64_e32 v[64:65], v[68:69]
	v_mov_b64_e32 v[60:61], v[68:69]
	v_mov_b64_e32 v[52:53], v[68:69]
	v_mov_b64_e32 v[78:79], v[66:67]
	v_mov_b64_e32 v[74:75], v[66:67]
	v_mov_b64_e32 v[70:71], v[66:67]
	v_mov_b64_e32 v[56:57], v[68:69]
	v_mov_b64_e32 v[102:103], v[66:67]
	v_lshlrev_b64 v[144:145], 11, v[186:187]
	s_or_b32 s20, s0, s1
	v_lshl_add_u64 v[188:189], s[36:37], 0, v[0:1]
	v_mov_b64_e32 v[106:107], v[66:67]
	s_waitcnt lgkmcnt(0)
	v_max_i32_e32 v143, v82, v84
	v_cmp_lt_i32_e32 vcc, 0, v143
	s_and_saveexec_b64 s[64:65], vcc
	s_cbranch_execz .LBB0_517
	s_lshl_b32 s0, s20, 1
	v_readlane_b32 s1, v243, 18
	s_add_u32 s0, s1, s0
	v_readlane_b32 s1, v243, 19
	s_addc_u32 s1, s1, 0
	v_cmp_eq_u32_e32 vcc, 0, v153
	v_lshl_add_u64 v[50:51], v[144:145], 1, s[0:1]
	v_lshl_add_u64 v[52:53], v[146:147], 1, s[0:1]
	s_ff1_i32_b32 s0, s4
	s_lshl_b32 s0, s0, 6
	s_cmp_lg_u32 s4, 0
	s_cselect_b32 s0, s0, 0xffffffc0
	s_ashr_i32 s1, s0, 31
	s_lshl_b64 s[38:39], s[0:1], 1
	v_lshl_add_u64 v[54:55], v[52:53], 0, s[38:39]
	v_lshl_add_u64 v[56:57], v[50:51], 0, s[38:39]
	v_lshl_add_u64 v[54:55], v[54:55], 0, v[0:1]
	v_lshl_add_u64 v[56:57], v[56:57], 0, v[0:1]
	global_load_dwordx4 v[86:89], v[54:55], off
	global_load_dwordx4 v[90:93], v[56:57], off
	v_add_u32_e32 v56, s0, v142
	v_mov_b64_e32 v[54:55], s[36:37]
	v_mad_i64_i32 v[56:57], s[38:39], v56, s72, v[54:55]
	v_add_u32_e32 v58, s0, v186
	v_lshl_add_u64 v[56:57], v[56:57], 0, v[0:1]
	v_mad_i64_i32 v[54:55], s[0:1], v58, s72, v[54:55]
	v_lshl_add_u64 v[54:55], v[54:55], 0, v[0:1]
	global_load_dwordx4 v[94:97], v[56:57], off offset:2048
	global_load_dwordx4 v[98:101], v[54:55], off offset:2048
	v_lshl_add_u64 v[148:149], v[50:51], 0, v[0:1]
	v_cndmask_b32_e32 v50, 0, v228, vcc
	s_movk_i32 s0, 0x90
	v_perm_b32 v82, v50, v50, s16
	v_mul_lo_u32 v50, v186, s0
	v_mov_b32_e32 v106, v1
	v_mov_b32_e32 v107, v1
	v_lshl_add_u64 v[150:151], v[52:53], 0, v[0:1]
	v_add_u32_e32 v158, s26, v50
	v_mov_b32_e32 v108, v1
	v_mov_b32_e32 v109, v1
	v_mov_b64_e32 v[102:103], v[106:107]
	v_mov_b64_e32 v[54:55], v[106:107]
	v_mov_b64_e32 v[70:71], v[106:107]
	v_mov_b64_e32 v[74:75], v[106:107]
	v_mov_b64_e32 v[78:79], v[106:107]
	v_mov_b64_e32 v[50:51], v[106:107]
	v_mov_b64_e32 v[58:59], v[106:107]
	v_mov_b64_e32 v[62:63], v[106:107]
	v_mov_b64_e32 v[66:67], v[106:107]
	s_mov_b32 s23, 0
	v_mov_b32_e32 v83, v82
	v_mov_b32_e32 v84, v82
	v_mov_b32_e32 v85, v82
	v_mov_b32_e32 v152, 0xf149f2ca
	s_mov_b64 s[66:67], 0
	v_mov_b64_e32 v[104:105], v[108:109]
	v_mov_b64_e32 v[56:57], v[108:109]
	v_mov_b64_e32 v[72:73], v[108:109]
	v_mov_b64_e32 v[76:77], v[108:109]
	v_mov_b64_e32 v[80:81], v[108:109]
	v_mov_b64_e32 v[52:53], v[108:109]
	v_mov_b64_e32 v[60:61], v[108:109]
	v_mov_b64_e32 v[64:65], v[108:109]
	v_mov_b64_e32 v[68:69], v[108:109]
	v_mov_b32_e32 v154, 0xf149f2ca
	v_readfirstlane_b32 s30, v220
	s_lshr_b32 s30, s30, 8
	s_cmp_lg_u32 s30, 1
	s_cbranch_scc1 .Lsel_skew_in
	s_barrier
	s_setprio 1

; DEVI void compute_S(f32x4 (&s)[2][4], const bf16x8 (&qf)[2][2], const bfu* Ks, int fr, int fq) {
; #pragma unroll
;   for (int g = 0; g < 2; ++g)
; #pragma unroll
;     for (int k = 0; k < 4; ++k) s[g][k] = f32x4{0.f, 0.f, 0.f, 0.f};
; #pragma unroll
;   for (int ks = 0; ks < 2; ++ks)
; #pragma unroll
;     for (int ksub = 0; ksub < 4; ++ksub) {
;       bf16x8 kf = *(const bf16x8*)(Ks + (ksub * 16 + fr) * LS + ks * 32 + fq * 8);
; #pragma unroll
;       for (int g = 0; g < 2; ++g) s[g][ksub] = __builtin_amdgcn_mfma_f32_16x16x32_bf16(kf, qf[g][ks], s[g][ksub], 0, 0, 0);
;     }
; }
; DEVI void attn_step(AttnState& st, const bf16x8 (&qf)[2][2], const bfu* Ks, const bfu* Vt, int hi, int lo, int fr, int fq) {
;   const int hi4 = hi - fq * 4, lo4 = lo - fq * 4;
;   f32x4 s[2][4];
;   compute_S(s, qf, Ks, fr, fq);
;   const bool anymask = __builtin_amdgcn_ballot_w64((hi < 63) || (lo >= 0)) != 0ull;
.LBB0_510:
	s_ff1_i32_b32 s4, s4
	v_lshrrev_b32_e32 v110, s4, v157
	v_and_b32_e32 v110, 1, v110
	v_cmp_eq_u32_e64 s[0:1], 1, v110
	v_bfe_u32 v110, v157, s4, 1
	v_cmp_ne_u32_e32 vcc, 0, v110
	s_cbranch_vccz .LBB0_502
	v_lshl_add_u32 v159, s23, 1, v155
	ds_read_b128 v[110:113], v159
	ds_read_b128 v[164:167], v159 offset:64
	s_cmp_eq_u32 s4, s25
	s_cselect_b64 vcc, -1, 0
	s_waitcnt lgkmcnt(1)
	v_mfma_f32_16x16x32_bf16 v[114:117], v[110:113], v[2:5], 0
	v_mfma_f32_16x16x32_bf16 v[118:121], v[110:113], v[10:13], 0
	ds_read_b128 v[110:113], v159 offset:2304
	s_waitcnt lgkmcnt(1)
	v_mfma_f32_16x16x32_bf16 v[118:121], v[164:167], v[14:17], v[118:121]
	s_waitcnt lgkmcnt(0)
	v_mfma_f32_16x16x32_bf16 v[122:125], v[110:113], v[2:5], 0
	v_mfma_f32_16x16x32_bf16 v[126:129], v[110:113], v[10:13], 0
	ds_read_b128 v[110:113], v159 offset:4608
	s_waitcnt lgkmcnt(0)
	v_mfma_f32_16x16x32_bf16 v[130:133], v[110:113], v[2:5], 0
	v_mfma_f32_16x16x32_bf16 v[134:137], v[110:113], v[10:13], 0
	ds_read_b128 v[110:113], v159 offset:6912
	s_waitcnt lgkmcnt(0)
	v_mfma_f32_16x16x32_bf16 v[138:141], v[110:113], v[2:5], 0
	v_mfma_f32_16x16x32_bf16 v[160:163], v[110:113], v[10:13], 0
	v_mfma_f32_16x16x32_bf16 v[110:113], v[164:167], v[6:9], v[114:117]
	ds_read_b128 v[164:167], v159 offset:2368
	s_waitcnt lgkmcnt(0)
	v_mfma_f32_16x16x32_bf16 v[114:117], v[164:167], v[6:9], v[122:125]
	v_mfma_f32_16x16x32_bf16 v[126:129], v[164:167], v[14:17], v[126:129]
	ds_read_b128 v[164:167], v159 offset:4672
	s_waitcnt lgkmcnt(0)
	v_mfma_f32_16x16x32_bf16 v[122:125], v[164:167], v[6:9], v[130:133]
	v_mfma_f32_16x16x32_bf16 v[130:133], v[164:167], v[14:17], v[134:137]
	ds_read_b128 v[164:167], v159 offset:6976
	s_waitcnt lgkmcnt(0)
	v_mfma_f32_16x16x32_bf16 v[134:137], v[164:167], v[6:9], v[138:141]
	s_nop 2
	v_cndmask_b32_e32 v138, 63, v177, vcc
	v_cndmask_b32_e64 v159, -1, v138, s[0:1]
	v_cmp_gt_i32_e32 vcc, 63, v159
	v_mfma_f32_16x16x32_bf16 v[138:141], v[164:167], v[14:17], v[160:163]
	s_mov_b64 s[38:39], -1
	s_cbranch_vccz .LBB0_513
	s_cmp_eq_u32 s4, s25
	s_cbranch_scc1 .Lsel_diag
	s_mov_b64 s[38:39], s[0:1]
	s_branch .LBB0_513

; template <bool WITH_L>
; DEVI void pv_accum_t(f32x4 (&o)[2][4], f32x4 (&ol)[2], const f32x4 (&pr)[2][4], const bfu* Vt, int fr, int fq) {
; #pragma unroll
;   for (int kp = 0; kp < 2; ++kp) {
;     bf16x8 pf[2];
; #pragma unroll
;     for (int g = 0; g < 2; ++g) {
;       uint4 u;
;       u.x = pack2(pr[g][2 * kp][0], pr[g][2 * kp][1]);
;       u.y = pack2(pr[g][2 * kp][2], pr[g][2 * kp][3]);
;       u.z = pack2(pr[g][2 * kp + 1][0], pr[g][2 * kp + 1][1]);
;       u.w = pack2(pr[g][2 * kp + 1][2], pr[g][2 * kp + 1][3]);
;       pf[g] = *(bf16x8*)&u;
;     }
;     if constexpr (WITH_L) {
;       const short one = (fr == 0) ? (short)0x3F80 : (short)0;
;       const bf16x8 vones = {one, one, one, one, one, one, one, one};
; #pragma unroll
;       for (int g = 0; g < 2; ++g) ol[g] = __builtin_amdgcn_mfma_f32_16x16x32_bf16(vones, pf[g], ol[g], 0, 0, 0);
;     }
; #pragma unroll
;     for (int dsub = 0; dsub < 4; ++dsub) {
;       uint2 lo = *(const uint2*)(Vt + (dsub * 16 + fr) * LS + (2 * kp) * 16 + fq * 4);
;       uint2 hi = *(const uint2*)(Vt + (dsub * 16 + fr) * LS + (2 * kp + 1) * 16 + fq * 4);
;       uint4 u; u.x = lo.x; u.y = lo.y; u.z = hi.x; u.w = hi.y;
;       bf16x8 vf = *(bf16x8*)&u;
; #pragma unroll
; DEVI void attn_step(AttnState& st, const bf16x8 (&qf)[2][2], const bfu* Ks, const bfu* Vt, int hi, int lo, int fr, int fq) {
;     ...
;   float scs[2];
; #pragma unroll
;   for (int g = 0; g < 2; ++g) {
;     float mx = NEGF;
; #pragma unroll
;     for (int ksub = 0; ksub < 4; ++ksub)
; #pragma unroll
;       for (int j = 0; j < 4; ++j) mx = fmaxf(mx, s[g][ksub][j]);
;     mx = fmaxf(mx, __shfl_xor(mx, 16));
;     mx = fmaxf(mx, __shfl_xor(mx, 32));
;     float mn = fmaxf(st.m[g], mx);
;     float sc = __builtin_amdgcn_exp2f(st.m[g] - mn);
; #pragma unroll
;     for (int ksub = 0; ksub < 4; ++ksub)
; #pragma unroll
;       for (int j = 0; j < 4; ++j) s[g][ksub][j] = __builtin_amdgcn_exp2f(s[g][ksub][j] - mn);
;     st.m[g] = mn;
;     scs[g] = sc;
;   }
;   if (__builtin_amdgcn_ballot_w64((scs[0] != 1.f) || (scs[1] != 1.f)) != 0ull) {
; #pragma unroll
;     for (int g = 0; g < 2; ++g) {
;       st.ol[g] *= scs[g];
; #pragma unroll
;       for (int dsub = 0; dsub < 4; ++dsub) st.o[g][dsub] *= scs[g];
;     }
;   }
;   pv_accum_t<true>(st.o, st.ol, s, Vt, fr, fq);
.LBB0_515:
	s_barrier
	v_sub_f32_e32 v126, v126, v248
	v_sub_f32_e32 v127, v127, v248
	v_sub_f32_e32 v116, v116, v247
	v_sub_f32_e32 v117, v117, v247
	v_sub_f32_e32 v110, v110, v247
	v_sub_f32_e32 v111, v111, v247
	v_sub_f32_e32 v112, v112, v247
	v_sub_f32_e32 v113, v113, v247
	v_exp_f32_e32 v126, v126
	v_exp_f32_e32 v127, v127
	v_exp_f32_e32 v116, v116
	v_exp_f32_e32 v117, v117
	v_exp_f32_e32 v110, v110
	v_exp_f32_e32 v111, v111
	v_exp_f32_e32 v112, v112
	v_exp_f32_e32 v113, v113
	v_sub_f32_e32 v118, v118, v248
	v_sub_f32_e32 v119, v119, v248
	v_sub_f32_e32 v120, v120, v248
	v_sub_f32_e32 v121, v121, v248
	v_sub_f32_e32 v114, v114, v247
	v_sub_f32_e32 v115, v115, v247
	v_exp_f32_e32 v118, v118
	v_exp_f32_e32 v119, v119
	v_exp_f32_e32 v120, v120
	v_exp_f32_e32 v121, v121
	v_exp_f32_e32 v114, v114
	v_exp_f32_e32 v115, v115
	v_cvt_pk_bf16_f32 v110, v110, v111
	v_cvt_pk_bf16_f32 v111, v112, v113
	v_cvt_pk_bf16_f32 v113, v116, v117
	v_cvt_pk_bf16_f32 v116, v126, v127
	v_lshl_add_u32 v126, s23, 1, v156
	v_add_u32_e32 v127, 0x4800, v126
	v_cvt_pk_bf16_f32 v112, v114, v115
	v_cvt_pk_bf16_f32 v114, v118, v119
	v_cvt_pk_bf16_f32 v115, v120, v121
	ds_read2_b64 v[118:121], v127 offset1:4
	v_sub_f32_e32 v128, v128, v248
	v_sub_f32_e32 v129, v129, v248
	v_exp_f32_e32 v128, v128
	v_exp_f32_e32 v129, v129
	s_waitcnt lgkmcnt(0)
	v_mfma_f32_16x16x32_bf16 v[66:69], v[118:121], v[110:113], v[66:69]
	v_cvt_pk_bf16_f32 v117, v128, v129
	v_add_u32_e32 v128, 0x5000, v126
	v_add_u32_e32 v129, 0x5800, v126
	v_mfma_f32_16x16x32_bf16 v[78:81], v[118:121], v[114:117], v[78:81]
	ds_read2_b64 v[118:121], v128 offset0:32 offset1:36
	v_add_u32_e32 v126, 0x6000, v126
	v_sub_f32_e32 v138, v138, v248
	s_waitcnt lgkmcnt(0)
	v_mfma_f32_16x16x32_bf16 v[62:65], v[118:121], v[110:113], v[62:65]
	v_sub_f32_e32 v139, v139, v248
	v_sub_f32_e32 v140, v140, v248
	v_sub_f32_e32 v141, v141, v248
	v_mfma_f32_16x16x32_bf16 v[74:77], v[118:121], v[114:117], v[74:77]
	ds_read2_b64 v[118:121], v129 offset0:64 offset1:68
	v_sub_f32_e32 v130, v130, v248
	v_sub_f32_e32 v131, v131, v248
	s_waitcnt lgkmcnt(0)
	v_mfma_f32_16x16x32_bf16 v[58:61], v[118:121], v[110:113], v[58:61]
	v_sub_f32_e32 v132, v132, v248
	v_sub_f32_e32 v133, v133, v248
	v_sub_f32_e32 v134, v134, v247
	v_mfma_f32_16x16x32_bf16 v[70:73], v[118:121], v[114:117], v[70:73]
	ds_read2_b64 v[118:121], v126 offset0:96 offset1:100
	v_sub_f32_e32 v135, v135, v247
	v_sub_f32_e32 v136, v136, v247
	s_waitcnt lgkmcnt(0)
	v_mfma_f32_16x16x32_bf16 v[50:53], v[118:121], v[110:113], v[50:53]
	v_sub_f32_e32 v137, v137, v247
	v_sub_f32_e32 v122, v122, v247
	v_sub_f32_e32 v123, v123, v247
	v_mfma_f32_16x16x32_bf16 v[54:57], v[118:121], v[114:117], v[54:57]
	ds_read2_b64 v[118:121], v127 offset0:8 offset1:12
	v_sub_f32_e32 v124, v124, v247
	v_sub_f32_e32 v125, v125, v247
	v_exp_f32_e32 v138, v138
	v_exp_f32_e32 v139, v139
	v_exp_f32_e32 v140, v140
	v_exp_f32_e32 v141, v141
	v_exp_f32_e32 v130, v130
	v_exp_f32_e32 v131, v131
	v_exp_f32_e32 v132, v132
	v_exp_f32_e32 v133, v133
	v_exp_f32_e32 v134, v134
	v_exp_f32_e32 v135, v135
	v_exp_f32_e32 v136, v136
	v_exp_f32_e32 v137, v137
	v_exp_f32_e32 v122, v122
	v_exp_f32_e32 v123, v123
	v_exp_f32_e32 v124, v124
	v_exp_f32_e32 v125, v125
	v_mfma_f32_16x16x32_bf16 v[102:105], v[82:85], v[110:113], v[102:105]
	v_cvt_pk_bf16_f32 v110, v122, v123
	v_cvt_pk_bf16_f32 v112, v134, v135
	v_cvt_pk_bf16_f32 v111, v124, v125
	v_mfma_f32_16x16x32_bf16 v[106:109], v[82:85], v[114:117], v[106:109]
	v_cvt_pk_bf16_f32 v113, v136, v137
	v_cvt_pk_bf16_f32 v114, v130, v131
	v_cvt_pk_bf16_f32 v115, v132, v133
	v_cvt_pk_bf16_f32 v116, v138, v139
	v_cvt_pk_bf16_f32 v117, v140, v141
	s_waitcnt lgkmcnt(0)
	v_mfma_f32_16x16x32_bf16 v[66:69], v[118:121], v[110:113], v[66:69]
	v_mfma_f32_16x16x32_bf16 v[78:81], v[118:121], v[114:117], v[78:81]
	ds_read2_b64 v[118:121], v128 offset0:40 offset1:44
	s_waitcnt lgkmcnt(0)
	v_mfma_f32_16x16x32_bf16 v[62:65], v[118:121], v[110:113], v[62:65]
	v_mfma_f32_16x16x32_bf16 v[74:77], v[118:121], v[114:117], v[74:77]
	ds_read2_b64 v[118:121], v129 offset0:72 offset1:76
	s_waitcnt lgkmcnt(0)
	v_mfma_f32_16x16x32_bf16 v[58:61], v[118:121], v[110:113], v[58:61]
	v_mfma_f32_16x16x32_bf16 v[70:73], v[118:121], v[114:117], v[70:73]
	ds_read2_b64 v[118:121], v126 offset0:104 offset1:108
	v_mfma_f32_16x16x32_bf16 v[102:105], v[82:85], v[110:113], v[102:105]
	v_mfma_f32_16x16x32_bf16 v[106:109], v[82:85], v[114:117], v[106:109]
	s_waitcnt lgkmcnt(0)
	v_mfma_f32_16x16x32_bf16 v[50:53], v[118:121], v[110:113], v[50:53]
	v_mfma_f32_16x16x32_bf16 v[54:57], v[118:121], v[114:117], v[54:57]
	s_branch .LBB0_503

; template <bool WITH_L>
; DEVI void pv_accum_t(f32x4 (&o)[2][4], f32x4 (&ol)[2], const f32x4 (&pr)[2][4], const bfu* Vt, int fr, int fq) {
; #pragma unroll
;   for (int kp = 0; kp < 2; ++kp) {
;     bf16x8 pf[2];
; #pragma unroll
;     for (int g = 0; g < 2; ++g) {
;       uint4 u;
;       u.x = pack2(pr[g][2 * kp][0], pr[g][2 * kp][1]);
;       u.y = pack2(pr[g][2 * kp][2], pr[g][2 * kp][3]);
;       u.z = pack2(pr[g][2 * kp + 1][0], pr[g][2 * kp + 1][1]);
;       u.w = pack2(pr[g][2 * kp + 1][2], pr[g][2 * kp + 1][3]);
;       pf[g] = *(bf16x8*)&u;
;     }
;     if constexpr (WITH_L) {
;       const short one = (fr == 0) ? (short)0x3F80 : (short)0;
;       const bf16x8 vones = {one, one, one, one, one, one, one, one};
; #pragma unroll
;       for (int g = 0; g < 2; ++g) ol[g] = __builtin_amdgcn_mfma_f32_16x16x32_bf16(vones, pf[g], ol[g], 0, 0, 0);
;     }
; #pragma unroll
;     for (int dsub = 0; dsub < 4; ++dsub) {
;       uint2 lo = *(const uint2*)(Vt + (dsub * 16 + fr) * LS + (2 * kp) * 16 + fq * 4);
;       uint2 hi = *(const uint2*)(Vt + (dsub * 16 + fr) * LS + (2 * kp + 1) * 16 + fq * 4);
;       uint4 u; u.x = lo.x; u.y = lo.y; u.z = hi.x; u.w = hi.y;
;       bf16x8 vf = *(bf16x8*)&u;
; #pragma unroll
;       for (int g = 0; g < 2; ++g) o[g][dsub] = __builtin_amdgcn_mfma_f32_16x16x32_bf16(vf, pf[g], o[g][dsub], 0, 0, 0);
;     }
;   }
; DEVI void nsa_item(const Params& p, int l, int item, char* lds_raw, volatile int* nsa_cnt) {
;     ...
;     for (; j <= qt; ++j) {
;       KV_STORE(kvo);
;       __syncthreads();
;       if (j < qt) {
;         int jn = j + 1;
;         KV_LOAD(kbase, vbase, jn);
;       }
;       attn_step(st, qf, Kb + kvo, Vb + kvo, (j == qt) ? tokl : 63, (j == qt - 8) ? tokl : -1, fr, fq);
;       kvo ^= 64 * LS;
;     }
.LBB0_525:
	s_barrier
	v_sub_f32_e32 v150, v150, v205
	v_sub_f32_e32 v151, v151, v205
	v_sub_f32_e32 v146, v146, v204
	v_sub_f32_e32 v147, v147, v204
	v_sub_f32_e32 v142, v142, v204
	v_sub_f32_e32 v143, v143, v204
	v_sub_f32_e32 v144, v144, v204
	v_sub_f32_e32 v145, v145, v204
	v_sub_f32_e32 v158, v158, v205
	v_sub_f32_e32 v159, v159, v205
	v_exp_f32_e32 v150, v150
	v_exp_f32_e32 v151, v151
	v_exp_f32_e32 v146, v146
	v_exp_f32_e32 v147, v147
	v_sub_f32_e32 v148, v148, v204
	v_sub_f32_e32 v149, v149, v204
	v_exp_f32_e32 v142, v142
	v_exp_f32_e32 v143, v143
	v_exp_f32_e32 v144, v144
	v_exp_f32_e32 v145, v145
	v_exp_f32_e32 v158, v158
	v_exp_f32_e32 v159, v159
	v_exp_f32_e32 v148, v148
	v_exp_f32_e32 v149, v149
	v_sub_f32_e32 v152, v152, v205
	v_sub_f32_e32 v153, v153, v205
	v_exp_f32_e32 v152, v152
	v_exp_f32_e32 v153, v153
	v_cvt_pk_bf16_f32 v142, v142, v143
	v_cvt_pk_bf16_f32 v143, v144, v145
	v_cvt_pk_bf16_f32 v144, v146, v147
	v_cvt_pk_bf16_f32 v146, v150, v151
	v_lshlrev_b32_e32 v150, 1, v203
	v_cvt_pk_bf16_f32 v145, v148, v149
	v_cvt_pk_bf16_f32 v148, v158, v159
	v_add3_u32 v158, v187, v199, v150
	v_add_u32_e32 v159, 0x4800, v158
	v_cvt_pk_bf16_f32 v147, v152, v153
	ds_read2_b64 v[150:153], v159 offset1:4
	v_sub_f32_e32 v160, v160, v205
	v_sub_f32_e32 v161, v161, v205
	v_exp_f32_e32 v160, v160
	v_exp_f32_e32 v161, v161
	s_waitcnt lgkmcnt(0)
	v_mfma_f32_16x16x32_bf16 v[110:113], v[150:153], v[142:145], v[110:113]
	v_cvt_pk_bf16_f32 v149, v160, v161
	v_add_u32_e32 v160, 0x5000, v158
	v_add_u32_e32 v161, 0x5800, v158
	v_mfma_f32_16x16x32_bf16 v[106:109], v[150:153], v[146:149], v[106:109]
	ds_read2_b64 v[150:153], v160 offset0:32 offset1:36
	v_add_u32_e32 v158, 0x6000, v158
	v_sub_f32_e32 v170, v170, v205
	s_waitcnt lgkmcnt(0)
	v_mfma_f32_16x16x32_bf16 v[102:105], v[150:153], v[142:145], v[102:105]
	v_sub_f32_e32 v171, v171, v205
	v_sub_f32_e32 v172, v172, v205
	v_sub_f32_e32 v173, v173, v205
	v_mfma_f32_16x16x32_bf16 v[98:101], v[150:153], v[146:149], v[98:101]
	ds_read2_b64 v[150:153], v161 offset0:64 offset1:68
	v_sub_f32_e32 v162, v162, v205
	v_sub_f32_e32 v163, v163, v205
	s_waitcnt lgkmcnt(0)
	v_mfma_f32_16x16x32_bf16 v[94:97], v[150:153], v[142:145], v[94:97]
	v_sub_f32_e32 v164, v164, v205
	v_sub_f32_e32 v165, v165, v205
	v_sub_f32_e32 v166, v166, v204
	v_mfma_f32_16x16x32_bf16 v[90:93], v[150:153], v[146:149], v[90:93]
	ds_read2_b64 v[150:153], v158 offset0:96 offset1:100
	v_sub_f32_e32 v167, v167, v204
	v_sub_f32_e32 v168, v168, v204
	s_waitcnt lgkmcnt(0)
	v_mfma_f32_16x16x32_bf16 v[86:89], v[150:153], v[142:145], v[86:89]
	v_sub_f32_e32 v169, v169, v204
	v_sub_f32_e32 v154, v154, v204
	v_sub_f32_e32 v155, v155, v204
	v_mfma_f32_16x16x32_bf16 v[82:85], v[150:153], v[146:149], v[82:85]
	ds_read2_b64 v[150:153], v159 offset0:8 offset1:12
	v_sub_f32_e32 v156, v156, v204
	v_sub_f32_e32 v157, v157, v204
	v_exp_f32_e32 v170, v170
	v_exp_f32_e32 v171, v171
	v_exp_f32_e32 v172, v172
	v_exp_f32_e32 v173, v173
	v_exp_f32_e32 v162, v162
	v_exp_f32_e32 v163, v163
	v_exp_f32_e32 v164, v164
	v_exp_f32_e32 v165, v165
	v_exp_f32_e32 v166, v166
	v_exp_f32_e32 v167, v167
	v_exp_f32_e32 v168, v168
	v_exp_f32_e32 v169, v169
	v_exp_f32_e32 v154, v154
	v_exp_f32_e32 v155, v155
	v_exp_f32_e32 v156, v156
	v_exp_f32_e32 v157, v157
	v_mfma_f32_16x16x32_bf16 v[138:141], v[114:117], v[142:145], v[138:141]
	v_cvt_pk_bf16_f32 v142, v154, v155
	v_cvt_pk_bf16_f32 v144, v166, v167
	v_cvt_pk_bf16_f32 v143, v156, v157
	v_mfma_f32_16x16x32_bf16 v[134:137], v[114:117], v[146:149], v[134:137]
	v_cvt_pk_bf16_f32 v145, v168, v169
	v_cvt_pk_bf16_f32 v146, v162, v163
	v_cvt_pk_bf16_f32 v147, v164, v165
	v_cvt_pk_bf16_f32 v148, v170, v171
	v_cvt_pk_bf16_f32 v149, v172, v173
	s_waitcnt lgkmcnt(0)
	v_mfma_f32_16x16x32_bf16 v[110:113], v[150:153], v[142:145], v[110:113]
	v_xor_b32_e32 v179, 0x1200, v179
	s_add_i32 s28, s28, 1
	s_add_i32 s30, s30, 64
	v_mfma_f32_16x16x32_bf16 v[106:109], v[150:153], v[146:149], v[106:109]
	ds_read2_b64 v[150:153], v160 offset0:40 offset1:44
	s_andn2_b64 vcc, exec, s[36:37]
	s_waitcnt lgkmcnt(0)
	v_mfma_f32_16x16x32_bf16 v[102:105], v[150:153], v[142:145], v[102:105]
	v_mfma_f32_16x16x32_bf16 v[98:101], v[150:153], v[146:149], v[98:101]
	ds_read2_b64 v[150:153], v161 offset0:72 offset1:76
	s_waitcnt lgkmcnt(0)
	v_mfma_f32_16x16x32_bf16 v[94:97], v[150:153], v[142:145], v[94:97]
	v_mfma_f32_16x16x32_bf16 v[90:93], v[150:153], v[146:149], v[90:93]
	ds_read2_b64 v[150:153], v158 offset0:104 offset1:108
	v_mfma_f32_16x16x32_bf16 v[138:141], v[114:117], v[142:145], v[138:141]
	v_mfma_f32_16x16x32_bf16 v[134:137], v[114:117], v[146:149], v[134:137]
	s_waitcnt lgkmcnt(0)
	v_mfma_f32_16x16x32_bf16 v[86:89], v[150:153], v[142:145], v[86:89]
	v_mfma_f32_16x16x32_bf16 v[82:85], v[150:153], v[146:149], v[82:85]
	s_cbranch_vccz .LBB0_479
	v_mov_b32_e32 v198, v204
	v_mov_b32_e32 v200, v205
	s_branch .LBB0_519
